# weight conversion: rows whose loads the compiler serialised are pre-loaded up front (same addresses) so the serialised loads hit the cache
# speedup vs baseline: 1.0071x; 1.0071x over previous
.LBB0_11:
	s_load_dwordx2 s[36:37], s[16:17], 0x10
	s_lshr_b32 s11, s11, 22
	s_mulk_i32 s11, 0x58
	s_sub_i32 s11, s3, s11
	s_lshl_b32 s14, s11, 7
	s_and_b32 s14, s14, 0x3ff80
	s_waitcnt lgkmcnt(0)
	s_add_u32 s36, s36, s14
	s_addc_u32 s37, s37, 0
	v_lshlrev_b32_e32 v4, 2, v2
	v_lshl_add_u64 v[58:59], s[36:37], 0, v[4:5]
	v_or_b32_e32 v250, s9, v67
	v_mad_u64_u32 v[248:249], s[36:37], v250, s0, v[58:59]
	global_load_dwordx4 v[244:247], v[248:249], off
	v_or_b32_e32 v250, s9, v69
	v_mad_u64_u32 v[248:249], s[36:37], v250, s0, v[58:59]
	global_load_dwordx4 v[244:247], v[248:249], off
	v_or_b32_e32 v250, s9, v71
	v_mad_u64_u32 v[248:249], s[36:37], v250, s0, v[58:59]
	global_load_dwordx4 v[244:247], v[248:249], off
	v_or_b32_e32 v250, s9, v73
	v_mad_u64_u32 v[248:249], s[36:37], v250, s0, v[58:59]
	global_load_dwordx4 v[244:247], v[248:249], off
	v_or_b32_e32 v250, s9, v75
	v_mad_u64_u32 v[248:249], s[36:37], v250, s0, v[58:59]
	global_load_dwordx4 v[244:247], v[248:249], off
	v_or_b32_e32 v250, s9, v77
	v_mad_u64_u32 v[248:249], s[36:37], v250, s0, v[58:59]
	global_load_dwordx4 v[244:247], v[248:249], off
	v_or_b32_e32 v250, s9, v78
	v_mad_u64_u32 v[248:249], s[36:37], v250, s0, v[58:59]
	global_load_dwordx4 v[244:247], v[248:249], off
	v_mad_u64_u32 v[84:85], s[36:37], v61, s0, v[58:59]
	global_load_dwordx4 v[84:87], v[84:85], off
	v_add_u32_e32 v4, v66, v81
	s_and_b64 vcc, exec, s[4:5]
	v_add_lshl_u32 v61, v65, s9, 2
	s_waitcnt vmcnt(0)
	v_pk_mul_f32 v[86:87], v[86:87], v[62:63] op_sel_hi:[1,0]
	v_pk_mul_f32 v[62:63], v[84:85], v[62:63] op_sel_hi:[1,0]
	ds_write2_b32 v4, v62, v63 offset1:1
	ds_write2_b32 v4, v86, v87 offset0:2 offset1:3
	s_cbranch_vccnz .LBB0_13
	global_load_dword v60, v61, s[18:19] offset:32

.LBB0_31:
	s_load_dwordx2 s[36:37], s[16:17], 0x30
	s_lshl_b32 s11, s3, 5
	s_and_b32 s11, s11, 0x7e0
	s_lshl_b32 s14, s11, 2
	v_lshlrev_b32_e32 v4, 2, v2
	s_waitcnt lgkmcnt(0)
	s_add_u32 s36, s36, s14
	s_addc_u32 s37, s37, 0
	v_lshl_add_u64 v[58:59], s[36:37], 0, v[4:5]
	v_or_b32_e32 v250, s9, v67
	v_mad_u64_u32 v[248:249], s[36:37], v250, s2, v[58:59]
	global_load_dwordx4 v[244:247], v[248:249], off
	v_or_b32_e32 v250, s9, v69
	v_mad_u64_u32 v[248:249], s[36:37], v250, s2, v[58:59]
	global_load_dwordx4 v[244:247], v[248:249], off
	v_or_b32_e32 v250, s9, v71
	v_mad_u64_u32 v[248:249], s[36:37], v250, s2, v[58:59]
	global_load_dwordx4 v[244:247], v[248:249], off
	v_or_b32_e32 v250, s9, v73
	v_mad_u64_u32 v[248:249], s[36:37], v250, s2, v[58:59]
	global_load_dwordx4 v[244:247], v[248:249], off
	v_or_b32_e32 v250, s9, v75
	v_mad_u64_u32 v[248:249], s[36:37], v250, s2, v[58:59]
	global_load_dwordx4 v[244:247], v[248:249], off
	v_mad_u64_u32 v[84:85], s[36:37], v61, s2, v[58:59]
	global_load_dwordx4 v[84:87], v[84:85], off
	v_add_u32_e32 v4, v66, v81
	s_and_b64 vcc, exec, s[4:5]
	v_add_lshl_u32 v61, s9, v65, 2
	s_waitcnt vmcnt(0)
	v_pk_mul_f32 v[86:87], v[86:87], v[62:63] op_sel_hi:[1,0]
	v_pk_mul_f32 v[62:63], v[84:85], v[62:63] op_sel_hi:[1,0]
	ds_write2_b32 v4, v62, v63 offset1:1
	ds_write2_b32 v4, v86, v87 offset0:2 offset1:3
	s_cbranch_vccnz .LBB0_33
	global_load_dword v60, v61, s[20:21] offset:32

.LBB0_46:
	s_load_dwordx2 s[36:37], s[16:17], 0x18
	s_lshr_b32 s14, s14, 22
	s_mulk_i32 s14, 0x58
	s_sub_i32 s11, s11, s14
	s_lshl_b32 s14, s11, 7
	s_and_b32 s14, s14, 0x3ff80
	s_waitcnt lgkmcnt(0)
	s_add_u32 s36, s36, s14
	s_addc_u32 s37, s37, 0
	v_lshlrev_b32_e32 v4, 2, v2
	v_lshl_add_u64 v[58:59], s[36:37], 0, v[4:5]
	v_or_b32_e32 v250, s9, v67
	v_mad_u64_u32 v[248:249], s[36:37], v250, s0, v[58:59]
	global_load_dwordx4 v[244:247], v[248:249], off
	v_or_b32_e32 v250, s9, v69
	v_mad_u64_u32 v[248:249], s[36:37], v250, s0, v[58:59]
	global_load_dwordx4 v[244:247], v[248:249], off
	v_or_b32_e32 v250, s9, v71
	v_mad_u64_u32 v[248:249], s[36:37], v250, s0, v[58:59]
	global_load_dwordx4 v[244:247], v[248:249], off
	v_or_b32_e32 v250, s9, v73
	v_mad_u64_u32 v[248:249], s[36:37], v250, s0, v[58:59]
	global_load_dwordx4 v[244:247], v[248:249], off
	v_or_b32_e32 v250, s9, v75
	v_mad_u64_u32 v[248:249], s[36:37], v250, s0, v[58:59]
	global_load_dwordx4 v[244:247], v[248:249], off
	v_or_b32_e32 v250, s9, v77
	v_mad_u64_u32 v[248:249], s[36:37], v250, s0, v[58:59]
	global_load_dwordx4 v[244:247], v[248:249], off
	v_or_b32_e32 v250, s9, v78
	v_mad_u64_u32 v[248:249], s[36:37], v250, s0, v[58:59]
	global_load_dwordx4 v[244:247], v[248:249], off
	v_mad_u64_u32 v[84:85], s[36:37], v61, s0, v[58:59]
	global_load_dwordx4 v[84:87], v[84:85], off
	v_add_u32_e32 v4, v66, v81
	s_and_b64 vcc, exec, s[4:5]
	v_add_lshl_u32 v61, v65, s9, 2
	s_waitcnt vmcnt(0)
	v_pk_mul_f32 v[86:87], v[86:87], v[62:63] op_sel_hi:[1,0]
	v_pk_mul_f32 v[62:63], v[84:85], v[62:63] op_sel_hi:[1,0]
	ds_write2_b32 v4, v62, v63 offset1:1
	ds_write2_b32 v4, v86, v87 offset0:2 offset1:3
	s_cbranch_vccnz .LBB0_48
	global_load_dword v60, v61, s[18:19] offset:32

.LBB0_872:
	s_load_dwordx2 s[6:7], s[44:45], 0x30
	s_lshl_b32 s31, s2, 5
	s_and_b32 s31, s31, 0xfe0
	s_lshl_b32 s33, s31, 2
	s_waitcnt lgkmcnt(0)
	s_add_u32 s6, s6, s33
	s_addc_u32 s7, s7, 0
	v_lshl_add_u64 v[16:17], s[6:7], 0, v[0:1]
	v_lshl_add_u64 v[16:17], v[16:17], 0, s[20:21]
	v_or_b32_e32 v250, s10, v19
	v_mad_u64_u32 v[248:249], s[6:7], v250, s27, v[16:17]
	global_load_dwordx4 v[244:247], v[248:249], off
	v_or_b32_e32 v250, s10, v21
	v_mad_u64_u32 v[248:249], s[6:7], v250, s27, v[16:17]
	global_load_dwordx4 v[244:247], v[248:249], off
	v_or_b32_e32 v250, s10, v22
	v_mad_u64_u32 v[248:249], s[6:7], v250, s27, v[16:17]
	global_load_dwordx4 v[244:247], v[248:249], off
	v_or_b32_e32 v250, s10, v23
	v_mad_u64_u32 v[248:249], s[6:7], v250, s27, v[16:17]
	global_load_dwordx4 v[244:247], v[248:249], off
	v_or_b32_e32 v250, s10, v24
	v_mad_u64_u32 v[248:249], s[6:7], v250, s27, v[16:17]
	global_load_dwordx4 v[244:247], v[248:249], off
	v_mad_u64_u32 v[32:33], s[6:7], v32, s27, v[16:17]
	global_load_dwordx4 v[32:35], v[32:33], off
	s_and_b64 vcc, exec, s[4:5]
	s_waitcnt vmcnt(0)
	v_pk_mul_f32 v[32:33], v[32:33], v[20:21] op_sel_hi:[1,0]
	v_pk_mul_f32 v[34:35], v[34:35], v[20:21] op_sel_hi:[1,0]
	ds_write2_b32 v29, v32, v33 offset1:1
	ds_write2_b32 v29, v34, v35 offset0:2 offset1:3
	v_add_lshl_u32 v32, s10, v9, 2
	s_cbranch_vccnz .LBB0_874
	global_load_dword v18, v32, s[12:13] offset:32

.LBB0_899:
	s_load_dwordx2 s[34:35], s[44:45], 0x128
	s_lshr_b32 s33, s33, 22
	s_mulk_i32 s33, 0x58
	s_sub_i32 s31, s31, s33
	s_lshl_b32 s33, s31, 7
	s_and_b32 s33, s33, 0x3ff80
	s_waitcnt lgkmcnt(0)
	s_add_u32 s34, s34, s33
	s_addc_u32 s35, s35, 0
	v_lshl_add_u64 v[16:17], s[34:35], 0, v[0:1]
	v_or_b32_e32 v250, s10, v19
	v_mad_u64_u32 v[248:249], s[34:35], v250, s29, v[16:17]
	global_load_dwordx4 v[244:247], v[248:249], off
	v_or_b32_e32 v250, s10, v21
	v_mad_u64_u32 v[248:249], s[34:35], v250, s29, v[16:17]
	global_load_dwordx4 v[244:247], v[248:249], off
	v_or_b32_e32 v250, s10, v22
	v_mad_u64_u32 v[248:249], s[34:35], v250, s29, v[16:17]
	global_load_dwordx4 v[244:247], v[248:249], off
	v_or_b32_e32 v250, s10, v23
	v_mad_u64_u32 v[248:249], s[34:35], v250, s29, v[16:17]
	global_load_dwordx4 v[244:247], v[248:249], off
	v_or_b32_e32 v250, s10, v24
	v_mad_u64_u32 v[248:249], s[34:35], v250, s29, v[16:17]
	global_load_dwordx4 v[244:247], v[248:249], off
	v_or_b32_e32 v250, s10, v25
	v_mad_u64_u32 v[248:249], s[34:35], v250, s29, v[16:17]
	global_load_dwordx4 v[244:247], v[248:249], off
	v_or_b32_e32 v250, s10, v26
	v_mad_u64_u32 v[248:249], s[34:35], v250, s29, v[16:17]
	global_load_dwordx4 v[244:247], v[248:249], off
	v_mad_u64_u32 v[32:33], s[34:35], v32, s29, v[16:17]
	global_load_dwordx4 v[32:35], v[32:33], off
	s_and_b64 vcc, exec, s[6:7]
	s_waitcnt vmcnt(0)
	v_pk_mul_f32 v[32:33], v[32:33], v[20:21] op_sel_hi:[1,0]
	v_pk_mul_f32 v[34:35], v[34:35], v[20:21] op_sel_hi:[1,0]
	ds_write2_b32 v29, v32, v33 offset1:1
	ds_write2_b32 v29, v34, v35 offset0:2 offset1:3
	v_add_lshl_u32 v32, v9, s10, 2
	s_cbranch_vccnz .LBB0_901
	global_load_dword v18, v32, s[14:15] offset:32

.LBB0_917:
	s_load_dwordx2 s[34:35], s[44:45], 0x130
	s_lshr_b32 s33, s33, 22
	s_mulk_i32 s33, 0x58
	s_sub_i32 s31, s31, s33
	s_lshl_b32 s33, s31, 7
	s_and_b32 s33, s33, 0x3ff80
	s_waitcnt lgkmcnt(0)
	s_add_u32 s34, s34, s33
	s_addc_u32 s35, s35, 0
	v_lshl_add_u64 v[16:17], s[34:35], 0, v[0:1]
	v_or_b32_e32 v250, s10, v19
	v_mad_u64_u32 v[248:249], s[34:35], v250, s29, v[16:17]
	global_load_dwordx4 v[244:247], v[248:249], off
	v_or_b32_e32 v250, s10, v21
	v_mad_u64_u32 v[248:249], s[34:35], v250, s29, v[16:17]
	global_load_dwordx4 v[244:247], v[248:249], off
	v_or_b32_e32 v250, s10, v22
	v_mad_u64_u32 v[248:249], s[34:35], v250, s29, v[16:17]
	global_load_dwordx4 v[244:247], v[248:249], off
	v_or_b32_e32 v250, s10, v23
	v_mad_u64_u32 v[248:249], s[34:35], v250, s29, v[16:17]
	global_load_dwordx4 v[244:247], v[248:249], off
	v_or_b32_e32 v250, s10, v24
	v_mad_u64_u32 v[248:249], s[34:35], v250, s29, v[16:17]
	global_load_dwordx4 v[244:247], v[248:249], off
	v_or_b32_e32 v250, s10, v25
	v_mad_u64_u32 v[248:249], s[34:35], v250, s29, v[16:17]
	global_load_dwordx4 v[244:247], v[248:249], off
	v_or_b32_e32 v250, s10, v26
	v_mad_u64_u32 v[248:249], s[34:35], v250, s29, v[16:17]
	global_load_dwordx4 v[244:247], v[248:249], off
	v_mad_u64_u32 v[32:33], s[34:35], v32, s29, v[16:17]
	global_load_dwordx4 v[32:35], v[32:33], off
	s_and_b64 vcc, exec, s[6:7]
	s_waitcnt vmcnt(0)
	v_pk_mul_f32 v[32:33], v[32:33], v[20:21] op_sel_hi:[1,0]
	v_pk_mul_f32 v[34:35], v[34:35], v[20:21] op_sel_hi:[1,0]
	ds_write2_b32 v29, v32, v33 offset1:1
	ds_write2_b32 v29, v34, v35 offset0:2 offset1:3
	v_add_lshl_u32 v32, v9, s10, 2
	s_cbranch_vccnz .LBB0_919
	global_load_dword v18, v32, s[14:15] offset:32

.LBB0_1702:
	s_load_dwordx2 s[48:49], s[10:11], 0x10
	s_lshr_b32 s37, s37, 22
	s_mulk_i32 s37, 0x58
	s_sub_i32 s37, s1, s37
	s_lshl_b32 s50, s37, 7
	s_and_b32 s50, s50, 0x3ff80
	s_waitcnt lgkmcnt(0)
	s_add_u32 s48, s48, s50
	s_addc_u32 s49, s49, 0
	v_lshlrev_b32_e32 v2, 2, v0
	v_lshl_add_u64 v[56:57], s[48:49], 0, v[2:3]
	v_lshl_add_u64 v[56:57], v[56:57], 0, s[26:27]
	v_or_b32_e32 v250, s8, v62
	v_mad_u64_u32 v[248:249], s[48:49], v250, s3, v[56:57]
	global_load_dwordx4 v[244:247], v[248:249], off
	v_or_b32_e32 v250, s8, v64
	v_mad_u64_u32 v[248:249], s[48:49], v250, s3, v[56:57]
	global_load_dwordx4 v[244:247], v[248:249], off
	v_or_b32_e32 v250, s8, v66
	v_mad_u64_u32 v[248:249], s[48:49], v250, s3, v[56:57]
	global_load_dwordx4 v[244:247], v[248:249], off
	v_or_b32_e32 v250, s8, v68
	v_mad_u64_u32 v[248:249], s[48:49], v250, s3, v[56:57]
	global_load_dwordx4 v[244:247], v[248:249], off
	v_or_b32_e32 v250, s8, v70
	v_mad_u64_u32 v[248:249], s[48:49], v250, s3, v[56:57]
	global_load_dwordx4 v[244:247], v[248:249], off
	v_or_b32_e32 v250, s8, v72
	v_mad_u64_u32 v[248:249], s[48:49], v250, s3, v[56:57]
	global_load_dwordx4 v[244:247], v[248:249], off
	v_or_b32_e32 v250, s8, v73
	v_mad_u64_u32 v[248:249], s[48:49], v250, s3, v[56:57]
	global_load_dwordx4 v[244:247], v[248:249], off
	v_mad_u64_u32 v[76:77], s[48:49], v76, s3, v[56:57]
	global_load_dwordx4 v[76:79], v[76:77], off
	v_add_u32_e32 v2, v59, v61
	s_and_b64 vcc, exec, s[4:5]
	s_waitcnt vmcnt(0)
	v_pk_mul_f32 v[76:77], v[76:77], v[60:61] op_sel_hi:[1,0]
	v_pk_mul_f32 v[78:79], v[78:79], v[60:61] op_sel_hi:[1,0]
	ds_write2_b32 v2, v76, v77 offset1:1
	ds_write2_b32 v2, v78, v79 offset0:2 offset1:3
	v_or_b32_e32 v2, s8, v62
	s_cbranch_vccnz .LBB0_1704
	v_lshlrev_b32_e32 v58, 2, v2
	global_load_dword v58, v58, s[12:13]

.LBB0_1722:
	s_load_dwordx2 s[48:49], s[10:11], 0x30
	s_lshl_b32 s37, s1, 5
	s_and_b32 s37, s37, 0x7e0
	s_lshl_b32 s50, s37, 2
	v_lshlrev_b32_e32 v2, 2, v0
	s_waitcnt lgkmcnt(0)
	s_add_u32 s48, s48, s50
	s_addc_u32 s49, s49, 0
	v_lshl_add_u64 v[56:57], s[48:49], 0, v[2:3]
	v_lshl_add_u64 v[56:57], v[56:57], 0, s[28:29]
	v_or_b32_e32 v250, s8, v62
	v_mad_u64_u32 v[248:249], s[48:49], v250, s36, v[56:57]
	global_load_dwordx4 v[244:247], v[248:249], off
	v_or_b32_e32 v250, s8, v64
	v_mad_u64_u32 v[248:249], s[48:49], v250, s36, v[56:57]
	global_load_dwordx4 v[244:247], v[248:249], off
	v_or_b32_e32 v250, s8, v66
	v_mad_u64_u32 v[248:249], s[48:49], v250, s36, v[56:57]
	global_load_dwordx4 v[244:247], v[248:249], off
	v_or_b32_e32 v250, s8, v68
	v_mad_u64_u32 v[248:249], s[48:49], v250, s36, v[56:57]
	global_load_dwordx4 v[244:247], v[248:249], off
	v_or_b32_e32 v250, s8, v70
	v_mad_u64_u32 v[248:249], s[48:49], v250, s36, v[56:57]
	global_load_dwordx4 v[244:247], v[248:249], off
	v_or_b32_e32 v250, s8, v72
	v_mad_u64_u32 v[248:249], s[48:49], v250, s36, v[56:57]
	global_load_dwordx4 v[244:247], v[248:249], off
	v_or_b32_e32 v250, s8, v73
	v_mad_u64_u32 v[248:249], s[48:49], v250, s36, v[56:57]
	global_load_dwordx4 v[244:247], v[248:249], off
	v_mad_u64_u32 v[76:77], s[48:49], v76, s36, v[56:57]
	global_load_dwordx4 v[76:79], v[76:77], off
	v_add_u32_e32 v2, v59, v61
	s_and_b64 vcc, exec, s[4:5]
	s_waitcnt vmcnt(0)
	v_pk_mul_f32 v[76:77], v[76:77], v[60:61] op_sel_hi:[1,0]
	v_pk_mul_f32 v[78:79], v[78:79], v[60:61] op_sel_hi:[1,0]
	ds_write2_b32 v2, v76, v77 offset1:1
	ds_write2_b32 v2, v78, v79 offset0:2 offset1:3
	v_or_b32_e32 v2, s8, v62
	s_cbranch_vccnz .LBB0_1724
	v_lshlrev_b32_e32 v58, 2, v2
	global_load_dword v58, v58, s[14:15]

.LBB0_1741:
	s_load_dwordx2 s[50:51], s[10:11], 0x18
	s_lshr_b32 s48, s48, 22
	s_mulk_i32 s48, 0x58
	s_sub_i32 s37, s37, s48
	s_lshl_b32 s48, s37, 7
	s_and_b32 s48, s48, 0x3ff80
	s_waitcnt lgkmcnt(0)
	s_add_u32 s48, s50, s48
	s_addc_u32 s49, s51, 0
	v_lshlrev_b32_e32 v2, 2, v0
	v_lshl_add_u64 v[56:57], s[48:49], 0, v[2:3]
	v_lshl_add_u64 v[56:57], v[56:57], 0, s[26:27]
	v_or_b32_e32 v250, s8, v62
	v_mad_u64_u32 v[248:249], s[48:49], v250, s3, v[56:57]
	global_load_dwordx4 v[244:247], v[248:249], off
	v_or_b32_e32 v250, s8, v64
	v_mad_u64_u32 v[248:249], s[48:49], v250, s3, v[56:57]
	global_load_dwordx4 v[244:247], v[248:249], off
	v_or_b32_e32 v250, s8, v66
	v_mad_u64_u32 v[248:249], s[48:49], v250, s3, v[56:57]
	global_load_dwordx4 v[244:247], v[248:249], off
	v_or_b32_e32 v250, s8, v68
	v_mad_u64_u32 v[248:249], s[48:49], v250, s3, v[56:57]
	global_load_dwordx4 v[244:247], v[248:249], off
	v_or_b32_e32 v250, s8, v70
	v_mad_u64_u32 v[248:249], s[48:49], v250, s3, v[56:57]
	global_load_dwordx4 v[244:247], v[248:249], off
	v_or_b32_e32 v250, s8, v72
	v_mad_u64_u32 v[248:249], s[48:49], v250, s3, v[56:57]
	global_load_dwordx4 v[244:247], v[248:249], off
	v_or_b32_e32 v250, s8, v73
	v_mad_u64_u32 v[248:249], s[48:49], v250, s3, v[56:57]
	global_load_dwordx4 v[244:247], v[248:249], off
	v_mad_u64_u32 v[76:77], s[48:49], v76, s3, v[56:57]
	global_load_dwordx4 v[76:79], v[76:77], off
	v_add_u32_e32 v2, v59, v61
	s_and_b64 vcc, exec, s[4:5]
	s_waitcnt vmcnt(0)
	v_pk_mul_f32 v[76:77], v[76:77], v[60:61] op_sel_hi:[1,0]
	v_pk_mul_f32 v[78:79], v[78:79], v[60:61] op_sel_hi:[1,0]
	ds_write2_b32 v2, v76, v77 offset1:1
	ds_write2_b32 v2, v78, v79 offset0:2 offset1:3
	v_or_b32_e32 v2, s8, v62
	s_cbranch_vccnz .LBB0_1743
	v_lshlrev_b32_e32 v58, 2, v2
	global_load_dword v58, v58, s[12:13]

.LBB0_2581:
	s_load_dwordx2 s[36:37], s[44:45], 0x30
	s_lshl_b32 s7, s2, 5
	s_and_b32 s7, s7, 0xfe0
	s_lshl_b32 s10, s7, 2
	s_waitcnt lgkmcnt(0)
	s_add_u32 s36, s36, s10
	s_addc_u32 s37, s37, 0
	v_lshl_add_u64 v[16:17], s[36:37], 0, v[0:1]
	v_lshl_add_u64 v[16:17], v[16:17], 0, s[20:21]
	v_or_b32_e32 v250, s6, v21
	v_mad_u64_u32 v[248:249], s[36:37], v250, s31, v[16:17]
	global_load_dwordx4 v[244:247], v[248:249], off
	v_or_b32_e32 v250, s6, v22
	v_mad_u64_u32 v[248:249], s[36:37], v250, s31, v[16:17]
	global_load_dwordx4 v[244:247], v[248:249], off
	v_or_b32_e32 v250, s6, v24
	v_mad_u64_u32 v[248:249], s[36:37], v250, s31, v[16:17]
	global_load_dwordx4 v[244:247], v[248:249], off
	v_or_b32_e32 v250, s6, v25
	v_mad_u64_u32 v[248:249], s[36:37], v250, s31, v[16:17]
	global_load_dwordx4 v[244:247], v[248:249], off
	v_or_b32_e32 v250, s6, v26
	v_mad_u64_u32 v[248:249], s[36:37], v250, s31, v[16:17]
	global_load_dwordx4 v[244:247], v[248:249], off
	v_or_b32_e32 v250, s6, v27
	v_mad_u64_u32 v[248:249], s[36:37], v250, s31, v[16:17]
	global_load_dwordx4 v[244:247], v[248:249], off
	v_or_b32_e32 v250, s6, v28
	v_mad_u64_u32 v[248:249], s[36:37], v250, s31, v[16:17]
	global_load_dwordx4 v[244:247], v[248:249], off
	v_mad_u64_u32 v[34:35], s[36:37], v33, s31, v[16:17]
	global_load_dwordx4 v[34:37], v[34:35], off
	s_and_b64 vcc, exec, s[4:5]
	s_waitcnt vmcnt(0)
	v_pk_mul_f32 v[36:37], v[36:37], v[20:21] op_sel_hi:[1,0]
	v_pk_mul_f32 v[34:35], v[34:35], v[20:21] op_sel_hi:[1,0]
	v_or_b32_e32 v20, s6, v21
	ds_write2_b32 v31, v34, v35 offset1:1
	ds_write2_b32 v31, v36, v37 offset0:2 offset1:3
	s_cbranch_vccnz .LBB0_2583
	v_lshlrev_b32_e32 v18, 2, v20
	global_load_dword v18, v18, s[12:13]

.LBB0_2606:
	s_load_dwordx2 s[48:49], s[44:45], 0x128
	s_lshr_b32 s37, s37, 22
	s_mulk_i32 s37, 0x58
	s_sub_i32 s36, s36, s37
	s_lshl_b32 s37, s36, 7
	s_and_b32 s37, s37, 0x3ff80
	s_waitcnt lgkmcnt(0)
	s_add_u32 s48, s48, s37
	s_addc_u32 s49, s49, 0
	v_lshl_add_u64 v[16:17], s[48:49], 0, v[0:1]
	v_lshl_add_u64 v[16:17], v[16:17], 0, s[22:23]
	v_or_b32_e32 v250, s10, v21
	v_mad_u64_u32 v[248:249], s[48:49], v250, s34, v[16:17]
	global_load_dwordx4 v[244:247], v[248:249], off
	v_or_b32_e32 v250, s10, v22
	v_mad_u64_u32 v[248:249], s[48:49], v250, s34, v[16:17]
	global_load_dwordx4 v[244:247], v[248:249], off
	v_or_b32_e32 v250, s10, v24
	v_mad_u64_u32 v[248:249], s[48:49], v250, s34, v[16:17]
	global_load_dwordx4 v[244:247], v[248:249], off
	v_or_b32_e32 v250, s10, v25
	v_mad_u64_u32 v[248:249], s[48:49], v250, s34, v[16:17]
	global_load_dwordx4 v[244:247], v[248:249], off
	v_or_b32_e32 v250, s10, v26
	v_mad_u64_u32 v[248:249], s[48:49], v250, s34, v[16:17]
	global_load_dwordx4 v[244:247], v[248:249], off
	v_or_b32_e32 v250, s10, v27
	v_mad_u64_u32 v[248:249], s[48:49], v250, s34, v[16:17]
	global_load_dwordx4 v[244:247], v[248:249], off
	v_or_b32_e32 v250, s10, v28
	v_mad_u64_u32 v[248:249], s[48:49], v250, s34, v[16:17]
	global_load_dwordx4 v[244:247], v[248:249], off
	v_mad_u64_u32 v[34:35], s[48:49], v33, s34, v[16:17]
	global_load_dwordx4 v[34:37], v[34:35], off
	s_and_b64 vcc, exec, s[6:7]
	s_waitcnt vmcnt(0)
	v_pk_mul_f32 v[36:37], v[36:37], v[20:21] op_sel_hi:[1,0]
	v_pk_mul_f32 v[34:35], v[34:35], v[20:21] op_sel_hi:[1,0]
	v_or_b32_e32 v20, s10, v21
	ds_write2_b32 v31, v34, v35 offset1:1
	ds_write2_b32 v31, v36, v37 offset0:2 offset1:3
	s_cbranch_vccnz .LBB0_2608
	v_lshlrev_b32_e32 v18, 2, v20
	global_load_dword v18, v18, s[14:15]

.LBB0_2624:
	s_load_dwordx2 s[48:49], s[44:45], 0x130
	s_lshr_b32 s37, s37, 22
	s_mulk_i32 s37, 0x58
	s_sub_i32 s36, s36, s37
	s_lshl_b32 s37, s36, 7
	s_and_b32 s37, s37, 0x3ff80
	s_waitcnt lgkmcnt(0)
	s_add_u32 s48, s48, s37
	s_addc_u32 s49, s49, 0
	v_lshl_add_u64 v[16:17], s[48:49], 0, v[0:1]
	v_lshl_add_u64 v[16:17], v[16:17], 0, s[22:23]
	v_or_b32_e32 v250, s10, v21
	v_mad_u64_u32 v[248:249], s[48:49], v250, s34, v[16:17]
	global_load_dwordx4 v[244:247], v[248:249], off
	v_or_b32_e32 v250, s10, v22
	v_mad_u64_u32 v[248:249], s[48:49], v250, s34, v[16:17]
	global_load_dwordx4 v[244:247], v[248:249], off
	v_or_b32_e32 v250, s10, v24
	v_mad_u64_u32 v[248:249], s[48:49], v250, s34, v[16:17]
	global_load_dwordx4 v[244:247], v[248:249], off
	v_or_b32_e32 v250, s10, v25
	v_mad_u64_u32 v[248:249], s[48:49], v250, s34, v[16:17]
	global_load_dwordx4 v[244:247], v[248:249], off
	v_or_b32_e32 v250, s10, v26
	v_mad_u64_u32 v[248:249], s[48:49], v250, s34, v[16:17]
	global_load_dwordx4 v[244:247], v[248:249], off
	v_or_b32_e32 v250, s10, v27
	v_mad_u64_u32 v[248:249], s[48:49], v250, s34, v[16:17]
	global_load_dwordx4 v[244:247], v[248:249], off
	v_or_b32_e32 v250, s10, v28
	v_mad_u64_u32 v[248:249], s[48:49], v250, s34, v[16:17]
	global_load_dwordx4 v[244:247], v[248:249], off
	v_mad_u64_u32 v[34:35], s[48:49], v33, s34, v[16:17]
	global_load_dwordx4 v[34:37], v[34:35], off
	s_and_b64 vcc, exec, s[6:7]
	s_waitcnt vmcnt(0)
	v_pk_mul_f32 v[36:37], v[36:37], v[20:21] op_sel_hi:[1,0]
	v_pk_mul_f32 v[34:35], v[34:35], v[20:21] op_sel_hi:[1,0]
	v_or_b32_e32 v20, s10, v21
	ds_write2_b32 v31, v34, v35 offset1:1
	ds_write2_b32 v31, v36, v37 offset0:2 offset1:3
	s_cbranch_vccnz .LBB0_2626
	v_lshlrev_b32_e32 v18, 2, v20
	global_load_dword v18, v18, s[14:15]
